# P5 EpiUp: row rstd statistics reused across consecutive column tiles that share the same 256-row tile (skips loads, shuffles and sqrt/div)
# speedup vs baseline: 1.0173x; 1.0047x over previous
; template <class Epi, class Sched, bool ALIGN_EPI = false, bool SP2 = false>
; __device__ __forceinline__ void gemm_phase(PG8_LAS unsigned char* lds, const Gemm g, const Sched& S, const Epi& E, int wave_s) {
;     ...
;     const int wid = __builtin_amdgcn_readfirstlane(tid >> 6), lane = tid & 63, wr = wid >> 2, wc = wid & 3, fr = lane & 15, fq = lane >> 4;
;     const int K = g.K, nt = K / BK;
;     unsigned voffA[2], voffB[2];
; #pragma unroll
;     for (int i = 0; i < 2; ++i) { int R, C; stage_rc(tid * 16 + i * 8192, R, C); const int Rb = Epi::PERM ? ((R & ~31) + perm32(R & 31)) : R;
;         voffA[i] = (unsigned)(R * K + C) * 2u; voffB[i] = (unsigned)(Rb * K + C) * 2u; }
;     const size_t kstep = (size_t)(BK * 2);
;     const size_t hstep = (size_t)HALF * K * 2;
;     const size_t tstep = 2 * hstep;
;     const unsigned ldsw = (unsigned)wid * 1024u;
;     const int aoff = lds_byte(wr * 64 + fr, fq * 8), boff = lds_byte(wc * 32 + fr, fq * 8);
;     ...
;     Unit cur, nxt; int ui = 0;
;     if (!S.next(0, cur)) return;
;     f32x4 acc[2][2][4][2];
; #pragma unroll
;     for (int a = 0; a < 2; ++a)
; #pragma unroll
;         for (int b = 0; b < 2; ++b)
; #pragma unroll
;             for (int m = 0; m < 4; ++m)
; #pragma unroll
;                 for (int n = 0; n < 2; ++n) acc[a][b][m][n] = (f32x4){0.f, 0.f, 0.f, 0.f};
;     bf16x8 At[4][2], B0[2][2], B1[2][2];
;     const char* cA = (const char*)g.A + (size_t)cur.pm * tstep; const char* cB = (const char*)g.Bt + (size_t)cur.pn * tstep;
;     S.a_ready(cur);
;     if constexpr (SP2) {
;         PG8_STAGE(PG8_SB(0, 0), cB, voffB); PG8_STAGE(PG8_SB(0, 1), cB + hstep, voffB); PG8_STAGE(PG8_SA(0, 0), cA, voffA); PG8_STAGE(PG8_SA(0, 1), cA + hstep, voffA);
;         if (wr == 1) PG8_BAR;
;         PG8_WAIT_V(2); PG8_BAR;
;         PG8_STAGE(PG8_SB(1, 0), cB + kstep, voffB); PG8_STAGE(PG8_SA(1, 0), cA + kstep, voffA); PG8_STAGE(PG8_SB(1, 1), cB + hstep + kstep, voffB);
;         PG8_WAIT_V(6); PG8_BAR;
;     } else {
;         PG8_STAGE(PG8_SB(0, 0), cB, voffB); PG8_STAGE(PG8_SA(0, 0), cA, voffA); PG8_STAGE(PG8_SB(0, 1), cB + hstep, voffB); PG8_STAGE(PG8_SA(0, 1), cA + hstep, voffA);
;         if (wr == 1) PG8_BAR;
;         PG8_WAIT_V(4); PG8_BAR;
;         PG8_STAGE(PG8_SB(1, 0), cB + kstep, voffB); PG8_STAGE(PG8_SA(1, 0), cA + kstep, voffA); PG8_STAGE(PG8_SB(1, 1), cB + hstep + kstep, voffB);
;         PG8_WAIT_V(6); PG8_BAR;
.LBB0_1248:
	s_mov_b32 s72, -1
	s_mov_b32 s2, s94
	s_mov_b32 s3, -1
	s_mov_b32 s42, -1
	v_mbcnt_lo_u32_b32 v0, s3, 0
	v_mbcnt_hi_u32_b32 v0, s3, v0
	v_lshl_add_u32 v10, s2, 6, v0
	s_cmpk_gt_i32 s14, 0xaff
	v_readfirstlane_b32 s3, v10
	s_cbranch_scc1 .LBB0_1264
	v_lshlrev_b32_e32 v0, 4, v10
	v_add_u32_e32 v1, 0x2000, v0
	v_ashrrev_i32_e32 v2, 31, v1
	v_lshrrev_b32_e32 v2, 22, v2
	v_add_u32_e32 v2, v1, v2
	v_ashrrev_i32_e32 v8, 10, v2
	v_mul_i32_i24_e32 v2, 0x400, v8
	v_sub_u32_e32 v1, v1, v2
	v_lshrrev_b32_e32 v2, 4, v1
	v_bitop3_b32 v1, v2, v1, 32 bitop3:0x6c
	v_ashrrev_i32_e32 v2, 31, v1
	v_lshrrev_b32_e32 v2, 26, v2
	v_add_u32_e32 v2, v1, v2
	v_lshlrev_b32_e32 v3, 3, v8
	v_ashrrev_i32_e32 v9, 6, v2
	v_and_b32_e32 v3, -16, v3
	v_add_u32_e32 v3, v9, v3
	v_and_b32_e32 v4, 3, v9
	s_mov_b32 s2, 0x1fffe0
	v_lshrrev_b32_e32 v5, 2, v3
	v_lshlrev_b32_e32 v6, 1, v3
	v_and_b32_e32 v2, 0xc0, v2
	v_and_or_b32 v4, v3, s2, v4
	v_and_b32_e32 v5, 4, v5
	v_and_b32_e32 v6, 24, v6
	v_sub_u32_e32 v1, v1, v2
	v_mov_b32_e32 v2, 1
	v_or3_b32 v4, v4, v5, v6
	v_lshlrev_b32_e32 v5, 5, v8
	v_ashrrev_i16_sdwa v1, v2, sext(v1) dst_sel:DWORD dst_unused:UNUSED_PAD src0_sel:DWORD src1_sel:BYTE_0
	v_and_b32_e32 v5, 32, v5
	v_bfe_i32 v11, v1, 0, 16
	v_add_lshl_u32 v1, v5, v11, 1
	v_lshl_add_u32 v128, v4, 11, v1
	s_waitcnt vmcnt(7)
	v_lshl_add_u32 v130, v3, 11, v1
	v_bfe_i32 v1, v10, 27, 1
	v_lshrrev_b32_e32 v1, 22, v1
	v_add_u32_e32 v1, v0, v1
	v_and_b32_e32 v1, 0xfffffc00, v1
	v_sub_u32_e32 v0, v0, v1
	v_lshrrev_b32_e32 v1, 4, v0
	v_ashrrev_i32_e32 v3, 31, v10
	v_bitop3_b32 v0, v1, v0, 32 bitop3:0x6c
	v_lshrrev_b32_e32 v3, 26, v3
	v_ashrrev_i32_e32 v1, 31, v0
	v_add_u32_e32 v3, v10, v3
	v_lshrrev_b32_e32 v1, 26, v1
	v_ashrrev_i32_e32 v13, 6, v3
	v_add_u32_e32 v1, v0, v1
	v_lshlrev_b32_e32 v3, 3, v13
	s_add_u32 s43, s34, 0x1700000
	v_ashrrev_i32_e32 v12, 6, v1
	v_and_b32_e32 v3, -16, v3
	s_addc_u32 s44, s35, 0
	v_add_u32_e32 v3, v12, v3
	v_and_b32_e32 v4, 3, v12
	s_ashr_i32 s46, s14, 31
	v_and_or_b32 v4, v3, s2, v4
	s_lshr_b32 s2, s46, 29
	s_add_i32 s2, s14, s2
	s_ashr_i32 s12, s3, 6
	s_ashr_i32 s4, s2, 3
	s_and_b32 s2, s2, -8
	s_ashr_i32 s16, s3, 8
	s_lshl_b32 s45, s12, 10
	s_sub_i32 s2, s14, s2
	s_cmp_lt_i32 s2, 0
	s_movk_i32 s47, 0x161
	s_cselect_b32 s5, s47, 0x160
	s_mul_i32 s2, s2, s5
	s_add_i32 s2, s2, s4
	s_mul_hi_i32 s4, s2, 0x2e8ba2e9
	s_lshr_b32 s5, s4, 31
	s_ashr_i32 s4, s4, 5
	s_add_i32 s4, s4, s5
	s_lshl_b32 s5, s4, 3
	s_mulk_i32 s4, 0xb0
	s_sub_i32 s4, s2, s4
	s_sext_i32_i16 s2, s4
	s_bfe_u32 s2, s2, 0x3001c
	s_add_i32 s10, s4, s2
	s_sext_i32_i16 s2, s10
	s_and_b32 s10, s10, 0xfff8
	s_sub_i32 s4, s4, s10
	s_sext_i32_i16 s4, s4
	v_lshrrev_b32_e32 v5, 2, v3
	v_lshlrev_b32_e32 v6, 1, v3
	v_and_b32_e32 v1, 0xc0, v1
	s_lshr_b32 s2, s2, 3
	s_add_i32 s4, s5, s4
	v_and_b32_e32 v5, 4, v5
	v_and_b32_e32 v6, 24, v6
	v_sub_u32_e32 v0, v0, v1
	s_ashr_i32 s5, s4, 31
	s_bfe_i64 s[18:19], s[2:3], 0x100000
	v_or3_b32 v4, v4, v5, v6
	v_lshlrev_b32_e32 v5, 5, v13
	v_ashrrev_i16_sdwa v0, v2, sext(v0) dst_sel:DWORD dst_unused:UNUSED_PAD src0_sel:DWORD src1_sel:BYTE_0
	s_lshl_b64 s[10:11], s[4:5], 19
	s_lshl_b64 s[18:19], s[18:19], 19
	v_and_b32_e32 v5, 32, v5
	v_bfe_i32 v14, v0, 0, 16
	s_add_u32 s38, s43, s18
	v_add_lshl_u32 v0, v5, v14, 1
	s_addc_u32 s39, s44, s19
	s_add_i32 s48, s45, 0
	v_lshl_add_u32 v132, v4, 11, v0
	s_add_i32 m0, s48, 0x10000
	s_waitcnt vmcnt(5)
	v_lshl_add_u32 v134, v3, 11, v0
	global_load_lds_dwordx4 v132, s[38:39]
	s_add_i32 m0, s48, 0x12000
	s_add_u32 s18, s38, 0x40000
	global_load_lds_dwordx4 v128, s[38:39]
	s_addc_u32 s19, s39, 0
	s_add_i32 m0, s48, 0x14000
	v_mov_b32_e32 v133, 0
	global_load_lds_dwordx4 v132, s[18:19]
	s_add_i32 m0, s48, 0x16000
	s_add_u32 s36, s28, s10
	s_addc_u32 s37, s29, s11
	s_add_i32 s49, s48, 0x2000
	global_load_lds_dwordx4 v128, s[18:19]
	s_mov_b32 m0, s48
	s_add_u32 s10, s36, 0x40000
	global_load_lds_dwordx4 v134, s[36:37]
	s_mov_b32 m0, s49
	s_addc_u32 s11, s37, 0
	s_add_i32 s50, s48, 0x4000
	global_load_lds_dwordx4 v130, s[36:37]
	s_mov_b32 m0, s50
	s_add_i32 s51, s48, 0x6000
	global_load_lds_dwordx4 v134, s[10:11]
	s_mov_b32 m0, s51
	v_mov_b32_e32 v129, v133
	global_load_lds_dwordx4 v130, s[10:11]
	v_mov_b32_e32 v135, v133
	v_mov_b32_e32 v131, v133
	s_cmp_eq_u32 s16, 1
	v_lshl_add_u64 v[6:7], s[38:39], 0, v[132:133]
	v_lshl_add_u64 v[4:5], s[38:39], 0, v[128:129]
	v_lshl_add_u64 v[0:1], s[36:37], 0, v[134:135]
	s_cselect_b64 s[10:11], -1, 0
	s_cmp_lg_u32 s16, 1
	v_lshl_add_u64 v[2:3], s[36:37], 0, v[130:131]
	s_cbranch_scc1 .LBB0_1251
	s_barrier

;     __device__ __forceinline__ void operator()(const pg8::f32x4 (&acc)[2][2][4][2], const Unit& u, int wr, int wc, int fr, int fq) const {
;     ...
;             for (int m = 0; m < 4; ++m) { const int row = rbase + ai * 128 + m * 16; const f32x4* sp = (const f32x4*)(SS + (size_t)row * 16);
;                 const f32x4 a = sp[0], b = sp[1], cc = sp[2], dd = sp[3];
;                 const float tot = ((a[0] + a[1]) + (a[2] + a[3])) + ((b[0] + b[1]) + (b[2] + b[3])) + ((cc[0] + cc[1]) + (cc[2] + cc[3])) + ((dd[0] + dd[1]) + (dd[2] + dd[3]));
;                 const float rstd = 1.f / sqrtf(tot * (1.f / D) + 1e-6f);
.LBB0_1260:
	v_lshl_add_u32 v144, s4, 8, v146
	s_cmp_eq_u32 s4, s72
	s_cbranch_scc1 .Lepiup_reuse
	v_mbcnt_lo_u32_b32 v214, -1, 0
	v_mbcnt_hi_u32_b32 v214, -1, v214
	v_and_b32_e32 v215, 48, v214
	v_and_b32_e32 v216, 15, v214
	v_lshl_add_u32 v220, v144, 6, v215
	v_lshlrev_b32_e32 v216, 2, v216
	v_add_u32_e32 v221, 0x2000, v220
	global_load_dwordx4 v[178:181], v220, s[18:19]
	global_load_dwordx4 v[182:185], v220, s[18:19] offset:1024
	global_load_dwordx4 v[186:189], v220, s[18:19] offset:2048
	global_load_dwordx4 v[190:193], v220, s[18:19] offset:3072
	global_load_dwordx4 v[194:197], v221, s[18:19]
	global_load_dwordx4 v[198:201], v221, s[18:19] offset:1024
	global_load_dwordx4 v[202:205], v221, s[18:19] offset:2048
	global_load_dwordx4 v[206:209], v221, s[18:19] offset:3072
	v_add_u32_e32 v217, 64, v216
	v_add_u32_e32 v218, 0x80, v216
	v_add_u32_e32 v219, 0xc0, v216
	s_waitcnt vmcnt(7)
	v_add_f32_e32 v178, v178, v179
	v_add_f32_e32 v180, v180, v181
	v_add_f32_e32 v178, v178, v180
	ds_bpermute_b32 v179, v216, v178
	ds_bpermute_b32 v180, v217, v178
	ds_bpermute_b32 v181, v218, v178
	ds_bpermute_b32 v236, v219, v178
	s_waitcnt vmcnt(6)
	v_add_f32_e32 v182, v182, v183
	v_add_f32_e32 v184, v184, v185
	v_add_f32_e32 v182, v182, v184
	ds_bpermute_b32 v183, v216, v182
	ds_bpermute_b32 v184, v217, v182
	ds_bpermute_b32 v185, v218, v182
	ds_bpermute_b32 v237, v219, v182
	s_waitcnt lgkmcnt(4)
	v_add_f32_e32 v228, v179, v180
	v_add_f32_e32 v228, v228, v181
	v_add_f32_e32 v228, v228, v236
	s_waitcnt vmcnt(5)
	v_add_f32_e32 v186, v186, v187
	v_add_f32_e32 v188, v188, v189
	v_add_f32_e32 v186, v186, v188
	ds_bpermute_b32 v187, v216, v186
	ds_bpermute_b32 v188, v217, v186
	ds_bpermute_b32 v189, v218, v186
	ds_bpermute_b32 v238, v219, v186
	s_waitcnt lgkmcnt(4)
	v_add_f32_e32 v229, v183, v184
	v_add_f32_e32 v229, v229, v185
	v_add_f32_e32 v229, v229, v237
	s_waitcnt vmcnt(4)
	v_add_f32_e32 v190, v190, v191
	v_add_f32_e32 v192, v192, v193
	v_add_f32_e32 v190, v190, v192
	ds_bpermute_b32 v191, v216, v190
	ds_bpermute_b32 v192, v217, v190
	ds_bpermute_b32 v193, v218, v190
	ds_bpermute_b32 v239, v219, v190
	s_waitcnt lgkmcnt(4)
	v_add_f32_e32 v230, v187, v188
	v_add_f32_e32 v230, v230, v189
	v_add_f32_e32 v230, v230, v238
	s_waitcnt vmcnt(3)
	v_add_f32_e32 v194, v194, v195
	v_add_f32_e32 v196, v196, v197
	v_add_f32_e32 v194, v194, v196
	ds_bpermute_b32 v195, v216, v194
	ds_bpermute_b32 v196, v217, v194
	ds_bpermute_b32 v197, v218, v194
	ds_bpermute_b32 v240, v219, v194
	s_waitcnt lgkmcnt(4)
	v_add_f32_e32 v231, v191, v192
	v_add_f32_e32 v231, v231, v193
	v_add_f32_e32 v231, v231, v239
	s_waitcnt vmcnt(2)
	v_add_f32_e32 v198, v198, v199
	v_add_f32_e32 v200, v200, v201
	v_add_f32_e32 v198, v198, v200
	ds_bpermute_b32 v199, v216, v198
	ds_bpermute_b32 v200, v217, v198
	ds_bpermute_b32 v201, v218, v198
	ds_bpermute_b32 v241, v219, v198
	s_waitcnt lgkmcnt(4)
	v_add_f32_e32 v232, v195, v196
	v_add_f32_e32 v232, v232, v197
	v_add_f32_e32 v232, v232, v240
	s_waitcnt vmcnt(1)
	v_add_f32_e32 v202, v202, v203
	v_add_f32_e32 v204, v204, v205
	v_add_f32_e32 v202, v202, v204
	ds_bpermute_b32 v203, v216, v202
	ds_bpermute_b32 v204, v217, v202
	ds_bpermute_b32 v205, v218, v202
	ds_bpermute_b32 v242, v219, v202
	s_waitcnt lgkmcnt(4)
	v_add_f32_e32 v233, v199, v200
	v_add_f32_e32 v233, v233, v201
	v_add_f32_e32 v233, v233, v241
	s_waitcnt vmcnt(0)
	v_add_f32_e32 v206, v206, v207
	v_add_f32_e32 v208, v208, v209
	v_add_f32_e32 v206, v206, v208
	ds_bpermute_b32 v207, v216, v206
	ds_bpermute_b32 v208, v217, v206
	ds_bpermute_b32 v209, v218, v206
	ds_bpermute_b32 v243, v219, v206
	s_waitcnt lgkmcnt(4)
	v_add_f32_e32 v234, v203, v204
	v_add_f32_e32 v234, v234, v205
	v_add_f32_e32 v234, v234, v242
	s_waitcnt lgkmcnt(0)
	v_add_f32_e32 v235, v207, v208
	v_add_f32_e32 v235, v235, v209
	v_add_f32_e32 v235, v235, v243
	v_cmp_eq_u32_e64 s[98:99], 16, v215
	v_cmp_eq_u32_e64 s[100:101], 32, v215
	v_cmp_eq_u32_e32 vcc, 48, v215
	s_nop 1
	v_cndmask_b32_e64 v244, v228, v230, s[98:99]
	v_cndmask_b32_e64 v245, v229, v231, s[98:99]
	v_cndmask_b32_e64 v244, v244, v232, s[100:101]
	v_cndmask_b32_e64 v245, v245, v233, s[100:101]
	v_cndmask_b32_e32 v244, v244, v234, vcc
	v_cndmask_b32_e32 v245, v245, v235, vcc
	v_fmamk_f32 v194, v244, 0x3a800000, v152
	v_mul_f32_e32 v195, 0x4f800000, v194
	v_cmp_gt_f32_e32 vcc, s62, v194
	s_nop 1
	v_cndmask_b32_e32 v195, v194, v195, vcc
	v_sqrt_f32_e32 v196, v195
	s_nop 0
	v_add_u32_e32 v197, -1, v196
	v_add_u32_e32 v198, 1, v196
	v_fma_f32 v199, -v197, v196, v195
	v_fma_f32 v200, -v198, v196, v195
	v_cmp_ge_f32_e64 s[98:99], 0, v199
	s_nop 1
	v_cndmask_b32_e64 v196, v196, v197, s[98:99]
	v_cmp_lt_f32_e64 s[98:99], 0, v200
	s_nop 1
	v_cndmask_b32_e64 v196, v196, v198, s[98:99]
	v_mul_f32_e32 v197, 0x37800000, v196
	v_cndmask_b32_e32 v196, v196, v197, vcc
	v_cmp_class_f32_e32 vcc, v195, v153
	s_nop 1
	v_cndmask_b32_e32 v197, v196, v195, vcc
	v_div_scale_f32 v198, s[98:99], v197, v197, 1.0
	v_rcp_f32_e32 v199, v198
	v_div_scale_f32 v200, vcc, 1.0, v197, 1.0
	v_fma_f32 v194, -v198, v199, 1.0
	v_fmac_f32_e32 v199, v194, v199
	v_mul_f32_e32 v194, v200, v199
	v_fma_f32 v195, -v198, v194, v200
	v_fmac_f32_e32 v194, v195, v199
	v_fma_f32 v198, -v198, v194, v200
	v_div_fmas_f32 v198, v198, v199, v194
	v_div_fixup_f32 v246, v198, v197, 1.0
	v_fmamk_f32 v201, v245, 0x3a800000, v152
	v_mul_f32_e32 v202, 0x4f800000, v201
	v_cmp_gt_f32_e32 vcc, s62, v201
	s_nop 1
	v_cndmask_b32_e32 v202, v201, v202, vcc
	v_sqrt_f32_e32 v203, v202
	s_nop 0
	v_add_u32_e32 v204, -1, v203
	v_add_u32_e32 v205, 1, v203
	v_fma_f32 v206, -v204, v203, v202
	v_fma_f32 v207, -v205, v203, v202
	v_cmp_ge_f32_e64 s[98:99], 0, v206
	s_nop 1
	v_cndmask_b32_e64 v203, v203, v204, s[98:99]
	v_cmp_lt_f32_e64 s[98:99], 0, v207
	s_nop 1
	v_cndmask_b32_e64 v203, v203, v205, s[98:99]
	v_mul_f32_e32 v204, 0x37800000, v203
	v_cndmask_b32_e32 v203, v203, v204, vcc
	v_cmp_class_f32_e32 vcc, v202, v153
	s_nop 1
	v_cndmask_b32_e32 v204, v203, v202, vcc
	v_div_scale_f32 v205, s[98:99], v204, v204, 1.0
	v_rcp_f32_e32 v206, v205
	v_div_scale_f32 v207, vcc, 1.0, v204, 1.0
	v_fma_f32 v201, -v205, v206, 1.0
	v_fmac_f32_e32 v206, v201, v206
	v_mul_f32_e32 v201, v207, v206
	v_fma_f32 v202, -v205, v201, v207
	v_fmac_f32_e32 v201, v202, v206
	v_fma_f32 v205, -v205, v201, v207
	v_div_fmas_f32 v205, v205, v206, v201
	v_div_fixup_f32 v247, v205, v204, 1.0
	ds_bpermute_b32 v178, v216, v246
	ds_bpermute_b32 v180, v216, v247
	ds_bpermute_b32 v182, v217, v246
	ds_bpermute_b32 v184, v217, v247
	ds_bpermute_b32 v186, v218, v246
	ds_bpermute_b32 v188, v218, v247
	ds_bpermute_b32 v190, v219, v246
	ds_bpermute_b32 v192, v219, v247
	s_waitcnt lgkmcnt(0)
	v_mov_b32_e32 v236, v178
	v_mov_b32_e32 v237, v180
	v_mov_b32_e32 v238, v182
	v_mov_b32_e32 v239, v184
	v_mov_b32_e32 v240, v186
	v_mov_b32_e32 v241, v188
	v_mov_b32_e32 v242, v190
	v_mov_b32_e32 v243, v192
	s_mov_b32 s72, s4
	s_branch .Lepiup_go
; __device__ __forceinline__ float silu_f(float x) { return x * sigm_f(x); }
;     __device__ __forceinline__ void operator()(const pg8::f32x4 (&acc)[2][2][4][2], const Unit& u, int wr, int wc, int fr, int fq) const {
;     ...
;                 f32x4 h0, h1;
; #pragma unroll
;                 for (int j = 0; j < 4; ++j) { h0[j] = silu_f(acc[ai][0][m][0][j] * rstd) * (acc[ai][1][m][0][j] * rstd); h1[j] = silu_f(acc[ai][0][m][1][j] * rstd) * (acc[ai][1][m][1][j] * rstd); }
;                 *(u32x4*)(HID + (size_t)row * DFF + col) = pack8(h0, h1); }
.Lepiup_reuse:
	v_mov_b32_e32 v178, v236
	v_mov_b32_e32 v180, v237
	v_mov_b32_e32 v182, v238
	v_mov_b32_e32 v184, v239
	v_mov_b32_e32 v186, v240
	v_mov_b32_e32 v188, v241
	v_mov_b32_e32 v190, v242
	v_mov_b32_e32 v192, v243
.Lepiup_go:
	v_ashrrev_i32_e32 v145, 31, v144
	v_lshlrev_b64 v[154:155], 6, v[144:145]
	v_lshl_add_u64 v[166:167], s[18:19], 0, v[154:155]
	v_mov_b32_e32 v174, v116
	v_mov_b32_e32 v175, v112
	v_mov_b32_e32 v112, v117
	v_mov_b32_e32 v177, v114
	v_mov_b32_e32 v176, v118
	v_mov_b32_e32 v172, v124
	v_mov_b32_e32 v124, v126
	v_lshl_or_b32 v170, s5, 7, v148
	v_mov_b32_e32 v173, v120
	v_mov_b32_e32 v120, v125
	v_mov_b32_e32 v125, v122
	v_mov_b32_e32 v122, v127
	v_ashrrev_i32_e32 v171, 31, v170
	s_nop 0
	s_nop 0
	s_nop 1
	v_mov_b32_e32 v114, v119
	s_nop 1
	s_nop 1
	s_nop 1
	v_lshl_add_u64 v[116:117], v[170:171], 1, s[30:31]
	v_pk_mul_f32 v[126:127], v[172:173], v[178:179] op_sel_hi:[1,0]
	v_pk_mul_f32 v[154:155], v[174:175], v[178:179] op_sel_hi:[1,0]
	v_pk_mul_f32 v[120:121], v[120:121], v[178:179] op_sel_hi:[1,0]
	v_pk_mul_f32 v[112:113], v[112:113], v[178:179] op_sel_hi:[1,0]
	v_pk_mul_f32 v[124:125], v[124:125], v[178:179] op_sel_hi:[1,0]
	v_pk_mul_f32 v[156:157], v[176:177], v[178:179] op_sel_hi:[1,0]
	v_pk_mul_f32 v[122:123], v[122:123], v[178:179] op_sel_hi:[1,0]
	v_pk_mul_f32 v[114:115], v[114:115], v[178:179] op_sel_hi:[1,0]
	v_mul_f32_e32 v118, 0xbfb8aa3b, v127
	v_mul_f32_e32 v119, 0xbfb8aa3b, v155
	v_mul_f32_e32 v145, 0xbfb8aa3b, v121
	v_mul_f32_e32 v158, 0xbfb8aa3b, v113
	v_mul_f32_e32 v159, 0xbfb8aa3b, v125
	v_mul_f32_e32 v161, 0xbfb8aa3b, v123
	v_mul_f32_e32 v162, 0xbfb8aa3b, v115
	v_exp_f32_e32 v118, v118
	v_exp_f32_e32 v119, v119
	v_exp_f32_e32 v145, v145
	v_exp_f32_e32 v158, v158
	v_exp_f32_e32 v159, v159
	v_mul_f32_e32 v160, 0xbfb8aa3b, v157
	v_exp_f32_e32 v161, v161
	v_exp_f32_e32 v162, v162
	v_exp_f32_e32 v160, v160
	v_add_f32_e32 v118, 1.0, v118
	v_add_f32_e32 v119, 1.0, v119
	v_add_f32_e32 v145, 1.0, v145
	v_add_f32_e32 v158, 1.0, v158
	v_add_f32_e32 v159, 1.0, v159
	v_add_f32_e32 v161, 1.0, v161
	v_add_f32_e32 v162, 1.0, v162
	v_rcp_f32_e32 v118, v118
	v_rcp_f32_e32 v119, v119
	v_rcp_f32_e32 v145, v145
	v_rcp_f32_e32 v158, v158
	v_rcp_f32_e32 v159, v159
	v_add_f32_e32 v160, 1.0, v160
	v_rcp_f32_e32 v161, v161
	v_rcp_f32_e32 v162, v162
	v_rcp_f32_e32 v160, v160
	v_mul_f32_e32 v118, v127, v118
	v_mul_f32_e32 v119, v155, v119
	v_mul_f32_e32 v121, v121, v145
	v_mul_f32_e32 v113, v113, v158
	v_mul_f32_e32 v125, v125, v159
	v_mul_f32_e32 v123, v123, v161
	v_mul_f32_e32 v115, v115, v162
	v_mul_f32_e32 v118, v126, v118
	v_mul_f32_e32 v119, v154, v119
	v_mul_f32_e32 v120, v120, v121
	v_mul_f32_e32 v121, v112, v113
	v_mul_f32_e32 v113, v124, v125
	v_mul_f32_e32 v127, v157, v160
	v_mul_f32_e32 v122, v122, v123
	v_mul_f32_e32 v115, v114, v115
	v_cvt_pk_bf16_f32 v112, v118, v120
	v_cvt_pk_bf16_f32 v113, v113, v122
	v_cvt_pk_bf16_f32 v114, v119, v121
	v_mad_i64_i32 v[118:119], s[4:5], v144, s63, v[116:117]
	v_mul_f32_e32 v124, v156, v127
	v_cvt_pk_bf16_f32 v115, v124, v115
	global_store_dwordx4 v[118:119], v[112:115], off
	v_mov_b32_e32 v127, v100
	v_mov_b32_e32 v100, v97
	v_or_b32_e32 v112, 16, v144
	v_ashrrev_i32_e32 v113, 31, v112
	v_lshlrev_b64 v[114:115], 6, v[112:113]
	v_lshl_add_u64 v[114:115], s[18:19], 0, v[114:115]
	v_mov_b32_e32 v114, v108
	v_mov_b32_e32 v115, v104
	v_mov_b32_e32 v104, v109
	v_mov_b32_e32 v97, v106
	v_mov_b32_e32 v126, v96
	v_mov_b32_e32 v96, v110
	s_nop 0
	s_nop 0
	v_mov_b32_e32 v109, v102
	s_nop 0
	v_mov_b32_e32 v108, v98
	v_mov_b32_e32 v106, v111
	s_nop 1
	s_nop 1
	v_mov_b32_e32 v102, v99
	s_nop 0
	v_pk_mul_f32 v[96:97], v[96:97], v[180:181] op_sel_hi:[1,0]
	v_pk_mul_f32 v[104:105], v[104:105], v[180:181] op_sel_hi:[1,0]
	v_pk_mul_f32 v[106:107], v[106:107], v[180:181] op_sel_hi:[1,0]
	v_mul_f32_e32 v119, 0xbfb8aa3b, v97
	v_pk_mul_f32 v[110:111], v[114:115], v[180:181] op_sel_hi:[1,0]
	v_pk_mul_f32 v[114:115], v[126:127], v[180:181] op_sel_hi:[1,0]
	v_pk_mul_f32 v[100:101], v[100:101], v[180:181] op_sel_hi:[1,0]
	v_pk_mul_f32 v[108:109], v[108:109], v[180:181] op_sel_hi:[1,0]
	v_pk_mul_f32 v[98:99], v[102:103], v[180:181] op_sel_hi:[1,0]
	v_mul_f32_e32 v113, 0xbfb8aa3b, v105
	v_mul_f32_e32 v121, 0xbfb8aa3b, v107
	v_exp_f32_e32 v119, v119
	v_mul_f32_e32 v118, 0xbfb8aa3b, v101
	v_mul_f32_e32 v120, 0xbfb8aa3b, v109
	v_mul_f32_e32 v122, 0xbfb8aa3b, v99
	v_exp_f32_e32 v113, v113
	v_exp_f32_e32 v121, v121
	v_mul_f32_e32 v102, 0xbfb8aa3b, v111
	v_mul_f32_e32 v103, 0xbfb8aa3b, v115
	v_exp_f32_e32 v118, v118
	v_exp_f32_e32 v120, v120
	v_exp_f32_e32 v122, v122
	v_exp_f32_e32 v102, v102
	v_exp_f32_e32 v103, v103
	v_add_f32_e32 v119, 1.0, v119
	v_add_f32_e32 v113, 1.0, v113
	v_add_f32_e32 v121, 1.0, v121
	v_rcp_f32_e32 v119, v119
	v_add_f32_e32 v118, 1.0, v118
	v_add_f32_e32 v120, 1.0, v120
	v_add_f32_e32 v122, 1.0, v122
	v_rcp_f32_e32 v113, v113
	v_rcp_f32_e32 v121, v121
	v_add_f32_e32 v102, 1.0, v102
	v_add_f32_e32 v103, 1.0, v103
	v_rcp_f32_e32 v118, v118
	v_rcp_f32_e32 v120, v120
	v_rcp_f32_e32 v122, v122
	v_rcp_f32_e32 v102, v102
	v_rcp_f32_e32 v103, v103
	v_mul_f32_e32 v97, v97, v119
	v_mul_f32_e32 v105, v105, v113
	v_mul_f32_e32 v97, v96, v97
	v_mul_f32_e32 v96, v107, v121
	v_mul_f32_e32 v101, v101, v118
	v_mul_f32_e32 v109, v109, v120
	v_mul_f32_e32 v104, v104, v105
	v_mul_f32_e32 v105, v106, v96
	v_mul_f32_e32 v96, v99, v122
	v_mul_f32_e32 v102, v111, v102
	v_mul_f32_e32 v103, v115, v103
	v_mul_f32_e32 v100, v100, v101
	v_mul_f32_e32 v101, v108, v109
	v_mul_f32_e32 v99, v98, v96
	v_mul_f32_e32 v102, v110, v102
	v_mul_f32_e32 v103, v114, v103
	v_cvt_pk_bf16_f32 v96, v102, v104
; __device__ __forceinline__ float silu_f(float x) { return x * sigm_f(x); }
;     __device__ __forceinline__ void operator()(const pg8::f32x4 (&acc)[2][2][4][2], const Unit& u, int wr, int wc, int fr, int fq) const {
;     ...
; #pragma unroll
;             for (int m = 0; m < 4; ++m) { const int row = rbase + ai * 128 + m * 16; const f32x4* sp = (const f32x4*)(SS + (size_t)row * 16);
;                 const f32x4 a = sp[0], b = sp[1], cc = sp[2], dd = sp[3];
;                 const float tot = ((a[0] + a[1]) + (a[2] + a[3])) + ((b[0] + b[1]) + (b[2] + b[3])) + ((cc[0] + cc[1]) + (cc[2] + cc[3])) + ((dd[0] + dd[1]) + (dd[2] + dd[3]));
;                 const float rstd = 1.f / sqrtf(tot * (1.f / D) + 1e-6f);
;                 f32x4 h0, h1;
; #pragma unroll
;                 for (int j = 0; j < 4; ++j) { h0[j] = silu_f(acc[ai][0][m][0][j] * rstd) * (acc[ai][1][m][0][j] * rstd); h1[j] = silu_f(acc[ai][0][m][1][j] * rstd) * (acc[ai][1][m][1][j] * rstd); }
;                 *(u32x4*)(HID + (size_t)row * DFF + col) = pack8(h0, h1); }
	v_cvt_pk_bf16_f32 v97, v97, v105
	v_cvt_pk_bf16_f32 v98, v103, v100
	v_cvt_pk_bf16_f32 v99, v101, v99
	v_mad_i64_i32 v[100:101], s[4:5], v112, s63, v[116:117]
	global_store_dwordx4 v[100:101], v[96:99], off
	v_mov_b32_e32 v114, v92
	v_mov_b32_e32 v115, v88
	v_or_b32_e32 v96, 32, v144
	v_ashrrev_i32_e32 v97, 31, v96
	v_lshlrev_b64 v[98:99], 6, v[96:97]
	v_lshl_add_u64 v[110:111], s[18:19], 0, v[98:99]
	v_mov_b32_e32 v88, v93
	v_mov_b32_e32 v119, v84
	v_mov_b32_e32 v84, v81
	v_mov_b32_e32 v81, v90
	v_mov_b32_e32 v118, v80
	v_mov_b32_e32 v80, v94
	s_nop 0
	s_nop 0
	v_mov_b32_e32 v93, v86
	s_nop 0
	v_mov_b32_e32 v92, v82
	v_mov_b32_e32 v90, v95
	s_nop 1
	s_nop 1
	v_mov_b32_e32 v86, v83
	s_nop 0
	v_pk_mul_f32 v[80:81], v[80:81], v[182:183] op_sel_hi:[1,0]
	v_pk_mul_f32 v[84:85], v[84:85], v[182:183] op_sel_hi:[1,0]
	v_mul_f32_e32 v101, 0xbfb8aa3b, v81
	v_mul_f32_e32 v100, 0xbfb8aa3b, v85
	v_exp_f32_e32 v101, v101
	v_exp_f32_e32 v100, v100
	v_pk_mul_f32 v[90:91], v[90:91], v[182:183] op_sel_hi:[1,0]
	v_pk_mul_f32 v[94:95], v[114:115], v[182:183] op_sel_hi:[1,0]
	v_add_f32_e32 v101, 1.0, v101
	v_pk_mul_f32 v[98:99], v[118:119], v[182:183] op_sel_hi:[1,0]
	v_pk_mul_f32 v[88:89], v[88:89], v[182:183] op_sel_hi:[1,0]
	v_pk_mul_f32 v[92:93], v[92:93], v[182:183] op_sel_hi:[1,0]
	v_pk_mul_f32 v[82:83], v[86:87], v[182:183] op_sel_hi:[1,0]
	v_mul_f32_e32 v103, 0xbfb8aa3b, v91
	v_add_f32_e32 v100, 1.0, v100
	v_rcp_f32_e32 v101, v101
	v_mul_f32_e32 v86, 0xbfb8aa3b, v95
	v_mul_f32_e32 v87, 0xbfb8aa3b, v99
	v_mul_f32_e32 v97, 0xbfb8aa3b, v89
	v_mul_f32_e32 v104, 0xbfb8aa3b, v83
	v_exp_f32_e32 v103, v103
	v_rcp_f32_e32 v100, v100
	v_mul_f32_e32 v102, 0xbfb8aa3b, v93
	v_exp_f32_e32 v86, v86
	v_exp_f32_e32 v87, v87
	v_exp_f32_e32 v97, v97
	v_exp_f32_e32 v104, v104
	v_exp_f32_e32 v102, v102
	v_mul_f32_e32 v81, v81, v101
	v_mul_f32_e32 v85, v85, v100
	v_mul_f32_e32 v81, v80, v81
	v_add_f32_e32 v80, 1.0, v103
	v_add_f32_e32 v86, 1.0, v86
	v_add_f32_e32 v87, 1.0, v87
	v_add_f32_e32 v97, 1.0, v97
	v_mul_f32_e32 v84, v84, v85
	v_rcp_f32_e32 v80, v80
	v_add_f32_e32 v85, 1.0, v104
	v_add_f32_e32 v102, 1.0, v102
	v_rcp_f32_e32 v86, v86
	v_rcp_f32_e32 v87, v87
	v_rcp_f32_e32 v97, v97
	v_rcp_f32_e32 v85, v85
	v_rcp_f32_e32 v102, v102
	v_mul_f32_e32 v80, v91, v80
	v_mul_f32_e32 v86, v95, v86
	v_mul_f32_e32 v87, v99, v87
	v_mul_f32_e32 v89, v89, v97
	v_mul_f32_e32 v90, v90, v80
	v_mul_f32_e32 v80, v83, v85
	v_mul_f32_e32 v93, v93, v102
	v_mul_f32_e32 v86, v94, v86
	v_mul_f32_e32 v87, v98, v87
	v_mul_f32_e32 v88, v88, v89
	v_mul_f32_e32 v83, v82, v80
	v_cvt_pk_bf16_f32 v80, v86, v88
	v_cvt_pk_bf16_f32 v81, v81, v90
	v_cvt_pk_bf16_f32 v82, v87, v84
	v_mad_i64_i32 v[84:85], s[4:5], v96, s63, v[116:117]
	v_mul_f32_e32 v89, v92, v93
	v_cvt_pk_bf16_f32 v83, v89, v83
	global_store_dwordx4 v[84:85], v[80:83], off
	v_mov_b32_e32 v98, v72
	v_mov_b32_e32 v99, v76
	v_or_b32_e32 v80, 48, v144
	v_ashrrev_i32_e32 v81, 31, v80
	v_lshlrev_b64 v[82:83], 6, v[80:81]
	v_lshl_add_u64 v[94:95], s[18:19], 0, v[82:83]
	v_mov_b32_e32 v76, v73
	v_mov_b32_e32 v101, v68
	v_mov_b32_e32 v68, v65
	v_mov_b32_e32 v100, v64
	v_mov_b32_e32 v64, v74
	s_nop 0
	s_nop 0
	v_mov_b32_e32 v73, v70
	s_nop 0
	v_mov_b32_e32 v72, v66
	v_mov_b32_e32 v65, v78
	v_mov_b32_e32 v78, v75
	s_nop 0
	s_nop 1
	s_nop 1
	v_pk_mul_f32 v[74:75], v[98:99], v[184:185] op_sel_hi:[1,0]
	v_pk_mul_f32 v[68:69], v[68:69], v[184:185] op_sel_hi:[1,0]
	v_pk_mul_f32 v[64:65], v[64:65], v[184:185] op_sel_hi:[1,0]
	v_mul_f32_e32 v70, 0xbfb8aa3b, v75
	v_mul_f32_e32 v85, 0xbfb8aa3b, v69
	v_mul_f32_e32 v86, 0xbfb8aa3b, v65
	v_exp_f32_e32 v70, v70
	v_exp_f32_e32 v85, v85
	v_exp_f32_e32 v86, v86
	v_pk_mul_f32 v[82:83], v[100:101], v[184:185] op_sel_hi:[1,0]
	v_add_f32_e32 v70, 1.0, v70
	v_add_f32_e32 v85, 1.0, v85
	v_add_f32_e32 v86, 1.0, v86
	v_rcp_f32_e32 v70, v70
	v_rcp_f32_e32 v85, v85
	v_rcp_f32_e32 v86, v86
	v_pk_mul_f32 v[76:77], v[76:77], v[184:185] op_sel_hi:[1,0]
	v_mul_f32_e32 v70, v75, v70
	v_mul_f32_e32 v69, v69, v85
	v_mul_f32_e32 v65, v65, v86
	v_mul_f32_e32 v74, v74, v70
	v_mov_b32_e32 v70, v67
	v_pk_mul_f32 v[72:73], v[72:73], v[184:185] op_sel_hi:[1,0]
	v_pk_mul_f32 v[78:79], v[78:79], v[184:185] op_sel_hi:[1,0]
	v_mul_f32_e32 v68, v68, v69
	v_mul_f32_e32 v69, v64, v65
	v_pk_mul_f32 v[64:65], v[70:71], v[184:185] op_sel_hi:[1,0]
	v_mul_f32_e32 v81, 0xbfb8aa3b, v83
	v_mul_f32_e32 v84, 0xbfb8aa3b, v77
	v_mul_f32_e32 v87, 0xbfb8aa3b, v73
	v_mul_f32_e32 v88, 0xbfb8aa3b, v79
	v_mul_f32_e32 v66, 0xbfb8aa3b, v65
	v_exp_f32_e32 v81, v81
	v_exp_f32_e32 v84, v84
	v_exp_f32_e32 v87, v87
	v_exp_f32_e32 v88, v88
	v_exp_f32_e32 v66, v66
	v_add_f32_e32 v81, 1.0, v81
	v_add_f32_e32 v84, 1.0, v84
	v_add_f32_e32 v87, 1.0, v87
	v_add_f32_e32 v70, 1.0, v88
	v_add_f32_e32 v66, 1.0, v66
	v_rcp_f32_e32 v81, v81
	v_rcp_f32_e32 v84, v84
	v_rcp_f32_e32 v87, v87
	v_rcp_f32_e32 v70, v70
	v_rcp_f32_e32 v66, v66
	v_mul_f32_e32 v75, v83, v81
	v_mul_f32_e32 v77, v77, v84
	v_mul_f32_e32 v67, v73, v87
	v_mul_f32_e32 v70, v79, v70
	v_mul_f32_e32 v65, v65, v66
	v_mul_f32_e32 v75, v82, v75
	v_mul_f32_e32 v76, v76, v77
	v_mul_f32_e32 v67, v72, v67
	v_mul_f32_e32 v70, v78, v70
	v_mul_f32_e32 v71, v64, v65
	v_cvt_pk_bf16_f32 v64, v74, v76
	v_cvt_pk_bf16_f32 v65, v69, v70
	v_cvt_pk_bf16_f32 v66, v75, v68
	v_mad_i64_i32 v[68:69], s[4:5], v80, s63, v[116:117]
	v_cvt_pk_bf16_f32 v67, v67, v71
	global_store_dwordx4 v[68:69], v[64:67], off
	v_mov_b32_e32 v82, v52
	v_mov_b32_e32 v83, v60
	v_add_u32_e32 v64, 0x80, v144
	v_ashrrev_i32_e32 v65, 31, v64
	v_lshlrev_b64 v[66:67], 6, v[64:65]
	v_lshl_add_u64 v[78:79], s[18:19], 0, v[66:67]
	v_mov_b32_e32 v84, v48
	v_mov_b32_e32 v85, v56
; __device__ __forceinline__ float silu_f(float x) { return x * sigm_f(x); }
;     __device__ __forceinline__ void operator()(const pg8::f32x4 (&acc)[2][2][4][2], const Unit& u, int wr, int wc, int fr, int fq) const {
;     ...
; #pragma unroll
;             for (int m = 0; m < 4; ++m) { const int row = rbase + ai * 128 + m * 16; const f32x4* sp = (const f32x4*)(SS + (size_t)row * 16);
;                 const f32x4 a = sp[0], b = sp[1], cc = sp[2], dd = sp[3];
;                 const float tot = ((a[0] + a[1]) + (a[2] + a[3])) + ((b[0] + b[1]) + (b[2] + b[3])) + ((cc[0] + cc[1]) + (cc[2] + cc[3])) + ((dd[0] + dd[1]) + (dd[2] + dd[3]));
;                 const float rstd = 1.f / sqrtf(tot * (1.f / D) + 1e-6f);
;                 f32x4 h0, h1;
; #pragma unroll
;                 for (int j = 0; j < 4; ++j) { h0[j] = silu_f(acc[ai][0][m][0][j] * rstd) * (acc[ai][1][m][0][j] * rstd); h1[j] = silu_f(acc[ai][0][m][1][j] * rstd) * (acc[ai][1][m][1][j] * rstd); }
;                 *(u32x4*)(HID + (size_t)row * DFF + col) = pack8(h0, h1); }
	v_mov_b32_e32 v60, v53
	v_mov_b32_e32 v56, v49
	v_mov_b32_e32 v52, v50
	s_nop 0
	s_nop 1
	v_mov_b32_e32 v48, v54
	v_mov_b32_e32 v49, v62
	s_nop 1
	s_nop 1
	s_nop 1
	v_mov_b32_e32 v53, v58
	v_pk_mul_f32 v[68:69], v[84:85], v[186:187] op_sel_hi:[1,0]
	v_pk_mul_f32 v[60:61], v[60:61], v[186:187] op_sel_hi:[1,0]
	v_pk_mul_f32 v[56:57], v[56:57], v[186:187] op_sel_hi:[1,0]
	v_pk_mul_f32 v[48:49], v[48:49], v[186:187] op_sel_hi:[1,0]
	v_mul_f32_e32 v58, 0xbfb8aa3b, v69
	v_mul_f32_e32 v62, 0xbfb8aa3b, v61
	v_mul_f32_e32 v65, 0xbfb8aa3b, v57
	v_mul_f32_e32 v70, 0xbfb8aa3b, v49
	v_exp_f32_e32 v58, v58
	v_exp_f32_e32 v62, v62
	v_exp_f32_e32 v65, v65
	v_exp_f32_e32 v70, v70
	v_add_f32_e32 v58, 1.0, v58
	v_add_f32_e32 v62, 1.0, v62
	v_add_f32_e32 v65, 1.0, v65
	v_add_f32_e32 v70, 1.0, v70
	v_rcp_f32_e32 v58, v58
	v_rcp_f32_e32 v62, v62
	v_rcp_f32_e32 v65, v65
	v_rcp_f32_e32 v70, v70
	v_mul_f32_e32 v58, v69, v58
	v_mul_f32_e32 v61, v61, v62
	v_mul_f32_e32 v57, v57, v65
	v_mul_f32_e32 v49, v49, v70
	v_mov_b32_e32 v62, v55
	v_mul_f32_e32 v65, v68, v58
	v_mul_f32_e32 v56, v56, v57
	v_mul_f32_e32 v57, v48, v49
	v_pk_mul_f32 v[48:49], v[62:63], v[186:187] op_sel_hi:[1,0]
	v_mov_b32_e32 v58, v51
	v_pk_mul_f32 v[66:67], v[82:83], v[186:187] op_sel_hi:[1,0]
	v_pk_mul_f32 v[52:53], v[52:53], v[186:187] op_sel_hi:[1,0]
	v_mul_f32_e32 v55, 0xbfb8aa3b, v49
	v_pk_mul_f32 v[50:51], v[58:59], v[186:187] op_sel_hi:[1,0]
	v_mul_f32_e32 v71, 0xbfb8aa3b, v53
	v_exp_f32_e32 v55, v55
	v_mul_f32_e32 v58, 0xbfb8aa3b, v51
	v_mul_f32_e32 v54, 0xbfb8aa3b, v67
	v_exp_f32_e32 v71, v71
	v_exp_f32_e32 v58, v58
	v_exp_f32_e32 v54, v54
	v_add_f32_e32 v55, 1.0, v55
	v_add_f32_e32 v71, 1.0, v71
	v_rcp_f32_e32 v55, v55
	v_add_f32_e32 v58, 1.0, v58
	v_add_f32_e32 v54, 1.0, v54
	v_mul_f32_e32 v60, v60, v61
	v_rcp_f32_e32 v61, v71
	v_rcp_f32_e32 v58, v58
	v_rcp_f32_e32 v54, v54
	v_mul_f32_e32 v49, v49, v55
	v_mul_f32_e32 v53, v53, v61
	v_mul_f32_e32 v49, v48, v49
	v_mul_f32_e32 v48, v51, v58
	v_mul_f32_e32 v54, v67, v54
	v_mul_f32_e32 v52, v52, v53
	v_mul_f32_e32 v51, v50, v48
	v_mul_f32_e32 v54, v66, v54
	v_cvt_pk_bf16_f32 v48, v54, v60
	v_cvt_pk_bf16_f32 v49, v57, v49
	v_cvt_pk_bf16_f32 v50, v65, v56
	v_cvt_pk_bf16_f32 v51, v52, v51
	v_mad_i64_i32 v[52:53], s[4:5], v64, s63, v[116:117]
	global_store_dwordx4 v[52:53], v[48:51], off
	v_mov_b32_e32 v66, v36
	v_mov_b32_e32 v67, v44
	v_add_u32_e32 v48, 0x90, v144
	v_ashrrev_i32_e32 v49, 31, v48
	v_lshlrev_b64 v[50:51], 6, v[48:49]
	v_lshl_add_u64 v[62:63], s[18:19], 0, v[50:51]
	v_mov_b32_e32 v68, v32
	v_mov_b32_e32 v69, v40
	v_mov_b32_e32 v44, v37
	v_mov_b32_e32 v40, v33
	v_mov_b32_e32 v36, v34
	s_nop 0
	s_nop 1
	v_mov_b32_e32 v32, v38
	v_mov_b32_e32 v33, v46
	s_nop 1
	s_nop 1
	s_nop 1
	v_mov_b32_e32 v37, v42
	v_pk_mul_f32 v[52:53], v[68:69], v[188:189] op_sel_hi:[1,0]
	v_pk_mul_f32 v[40:41], v[40:41], v[188:189] op_sel_hi:[1,0]
	v_mul_f32_e32 v42, 0xbfb8aa3b, v53
	v_mul_f32_e32 v49, 0xbfb8aa3b, v41
	v_exp_f32_e32 v42, v42
	v_exp_f32_e32 v49, v49
	v_pk_mul_f32 v[32:33], v[32:33], v[188:189] op_sel_hi:[1,0]
	v_pk_mul_f32 v[44:45], v[44:45], v[188:189] op_sel_hi:[1,0]
	v_mul_f32_e32 v54, 0xbfb8aa3b, v33
	v_mul_f32_e32 v46, 0xbfb8aa3b, v45
	v_exp_f32_e32 v54, v54
	v_add_f32_e32 v42, 1.0, v42
	v_exp_f32_e32 v46, v46
	v_add_f32_e32 v49, 1.0, v49
	v_rcp_f32_e32 v42, v42
	v_rcp_f32_e32 v49, v49
	v_pk_mul_f32 v[36:37], v[36:37], v[188:189] op_sel_hi:[1,0]
	v_add_f32_e32 v54, 1.0, v54
	v_mul_f32_e32 v55, 0xbfb8aa3b, v37
	v_add_f32_e32 v46, 1.0, v46
	v_rcp_f32_e32 v54, v54
	v_mul_f32_e32 v42, v53, v42
	v_rcp_f32_e32 v46, v46
	v_mul_f32_e32 v41, v41, v49
	v_mul_f32_e32 v49, v52, v42
	v_exp_f32_e32 v42, v55
	v_mul_f32_e32 v33, v33, v54
	v_mul_f32_e32 v45, v45, v46
	v_mul_f32_e32 v40, v40, v41
	v_mul_f32_e32 v41, v32, v33
	v_add_f32_e32 v32, 1.0, v42
	v_mov_b32_e32 v46, v39
	v_mul_f32_e32 v44, v44, v45
	v_rcp_f32_e32 v45, v32
	v_pk_mul_f32 v[32:33], v[46:47], v[188:189] op_sel_hi:[1,0]
	v_mov_b32_e32 v42, v35
	v_pk_mul_f32 v[50:51], v[66:67], v[188:189] op_sel_hi:[1,0]
	v_mul_f32_e32 v39, 0xbfb8aa3b, v33
	v_pk_mul_f32 v[34:35], v[42:43], v[188:189] op_sel_hi:[1,0]
	v_exp_f32_e32 v39, v39
	v_mul_f32_e32 v42, 0xbfb8aa3b, v35
	v_mul_f32_e32 v38, 0xbfb8aa3b, v51
	v_exp_f32_e32 v42, v42
	v_exp_f32_e32 v38, v38
	v_add_f32_e32 v39, 1.0, v39
	v_rcp_f32_e32 v39, v39
	v_add_f32_e32 v42, 1.0, v42
	v_add_f32_e32 v38, 1.0, v38
	v_rcp_f32_e32 v42, v42
	v_rcp_f32_e32 v38, v38
	v_mul_f32_e32 v33, v33, v39
	v_mul_f32_e32 v37, v37, v45
	v_mul_f32_e32 v33, v32, v33
	v_mul_f32_e32 v32, v35, v42
	v_mul_f32_e32 v38, v51, v38
	v_mul_f32_e32 v36, v36, v37
	v_mul_f32_e32 v35, v34, v32
	v_mul_f32_e32 v38, v50, v38
	v_cvt_pk_bf16_f32 v32, v38, v44
	v_cvt_pk_bf16_f32 v33, v41, v33
	v_cvt_pk_bf16_f32 v34, v49, v40
	v_cvt_pk_bf16_f32 v35, v36, v35
	v_mad_i64_i32 v[36:37], s[4:5], v48, s63, v[116:117]
	v_add_u32_e32 v48, 0xa0, v144
	v_ashrrev_i32_e32 v49, 31, v48
	global_store_dwordx4 v[36:37], v[32:35], off
	v_mov_b32_e32 v52, v16
	v_mov_b32_e32 v50, v20
	v_lshlrev_b64 v[32:33], 6, v[48:49]
; #define PG8_BAR __builtin_amdgcn_s_barrier()
; __device__ __forceinline__ float silu_f(float x) { return x * sigm_f(x); }
; template <class Epi, class Sched, bool ALIGN_EPI = false, bool SP2 = false>
; __device__ __forceinline__ void gemm_phase(PG8_LAS unsigned char* lds, const Gemm g, const Sched& S, const Epi& E, int wave_s) {
;     ...
;         if constexpr (ALIGN_EPI) { if (wr == 0) PG8_BAR; }
;         if constexpr (!Epi::AFTER_DRAIN) { E(acc, cur, wr, wc, fr, fq); S.done(cur); }
;         if (!has_next) break;
; #pragma unroll
;         for (int a = 0; a < 2; ++a)
; #pragma unroll
;             for (int b = 0; b < 2; ++b)
; #pragma unroll
;                 for (int m = 0; m < 4; ++m)
; #pragma unroll
;                     for (int n = 0; n < 2; ++n) acc[a][b][m][n] = (f32x4){0.f, 0.f, 0.f, 0.f};
;         cur = nxt; cA = nA; cB = nB; ++ui;
;         if constexpr (ALIGN_EPI) { if (wr == 1) PG8_BAR; }
;     __device__ __forceinline__ void operator()(const pg8::f32x4 (&acc)[2][2][4][2], const Unit& u, int wr, int wc, int fr, int fq) const {
;     ...
; #pragma unroll
;             for (int m = 0; m < 4; ++m) { const int row = rbase + ai * 128 + m * 16; const f32x4* sp = (const f32x4*)(SS + (size_t)row * 16);
;                 const f32x4 a = sp[0], b = sp[1], cc = sp[2], dd = sp[3];
;                 const float tot = ((a[0] + a[1]) + (a[2] + a[3])) + ((b[0] + b[1]) + (b[2] + b[3])) + ((cc[0] + cc[1]) + (cc[2] + cc[3])) + ((dd[0] + dd[1]) + (dd[2] + dd[3]));
;                 const float rstd = 1.f / sqrtf(tot * (1.f / D) + 1e-6f);
;                 f32x4 h0, h1;
; #pragma unroll
;                 for (int j = 0; j < 4; ++j) { h0[j] = silu_f(acc[ai][0][m][0][j] * rstd) * (acc[ai][1][m][0][j] * rstd); h1[j] = silu_f(acc[ai][0][m][1][j] * rstd) * (acc[ai][1][m][1][j] * rstd); }
;                 *(u32x4*)(HID + (size_t)row * DFF + col) = pack8(h0, h1); }
	v_lshl_add_u64 v[44:45], s[18:19], 0, v[32:33]
	v_mov_b32_e32 v53, v24
	v_mov_b32_e32 v24, v17
	v_mov_b32_e32 v51, v28
	v_mov_b32_e32 v28, v21
	s_nop 0
	s_nop 0
	s_nop 1
	v_mov_b32_e32 v16, v22
	s_nop 1
	s_nop 1
	s_nop 1
	v_mov_b32_e32 v17, v30
	v_pk_mul_f32 v[32:33], v[50:51], v[190:191] op_sel_hi:[1,0]
	v_pk_mul_f32 v[28:29], v[28:29], v[190:191] op_sel_hi:[1,0]
	v_pk_mul_f32 v[34:35], v[52:53], v[190:191] op_sel_hi:[1,0]
	v_pk_mul_f32 v[24:25], v[24:25], v[190:191] op_sel_hi:[1,0]
	v_pk_mul_f32 v[16:17], v[16:17], v[190:191] op_sel_hi:[1,0]
	v_mul_f32_e32 v21, 0xbfb8aa3b, v33
	v_mul_f32_e32 v30, 0xbfb8aa3b, v29
	v_exp_f32_e32 v21, v21
	v_exp_f32_e32 v30, v30
	v_mul_f32_e32 v36, 0xbfb8aa3b, v25
	v_mul_f32_e32 v37, 0xbfb8aa3b, v17
	v_add_f32_e32 v21, 1.0, v21
	v_add_f32_e32 v30, 1.0, v30
	v_rcp_f32_e32 v21, v21
	v_rcp_f32_e32 v30, v30
	v_exp_f32_e32 v36, v36
	v_exp_f32_e32 v37, v37
	v_mul_f32_e32 v21, v33, v21
	v_mul_f32_e32 v29, v29, v30
	v_mul_f32_e32 v21, v32, v21
	v_mul_f32_e32 v32, v28, v29
	v_mov_b32_e32 v28, v18
	v_mov_b32_e32 v29, v26
	v_add_f32_e32 v36, 1.0, v36
	v_add_f32_e32 v37, 1.0, v37
	v_pk_mul_f32 v[28:29], v[28:29], v[190:191] op_sel_hi:[1,0]
	v_rcp_f32_e32 v36, v36
	v_rcp_f32_e32 v30, v37
	v_mul_f32_e32 v18, 0xbfb8aa3b, v29
	v_exp_f32_e32 v18, v18
	v_mul_f32_e32 v25, v25, v36
	v_mul_f32_e32 v17, v17, v30
	v_mul_f32_e32 v24, v24, v25
	v_mul_f32_e32 v25, v16, v17
	v_add_f32_e32 v16, 1.0, v18
	v_mov_b32_e32 v30, v23
	v_rcp_f32_e32 v33, v16
	v_pk_mul_f32 v[16:17], v[30:31], v[190:191] op_sel_hi:[1,0]
	v_mov_b32_e32 v26, v19
	v_mul_f32_e32 v18, 0xbfb8aa3b, v17
	v_exp_f32_e32 v23, v18
	v_pk_mul_f32 v[18:19], v[26:27], v[190:191] op_sel_hi:[1,0]
	v_mul_f32_e32 v22, 0xbfb8aa3b, v35
	v_mul_f32_e32 v20, 0xbfb8aa3b, v19
	v_exp_f32_e32 v20, v20
	v_exp_f32_e32 v22, v22
	v_add_f32_e32 v23, 1.0, v23
	v_rcp_f32_e32 v23, v23
	v_add_f32_e32 v20, 1.0, v20
	v_rcp_f32_e32 v20, v20
	v_add_f32_e32 v22, 1.0, v22
	v_rcp_f32_e32 v22, v22
	v_mul_f32_e32 v17, v17, v23
	v_mul_f32_e32 v17, v16, v17
	v_mul_f32_e32 v16, v19, v20
	v_mul_f32_e32 v19, v18, v16
	v_cvt_pk_bf16_f32 v16, v21, v32
	v_add_u32_e32 v32, 0xb0, v144
	v_mul_f32_e32 v22, v35, v22
	v_mul_f32_e32 v26, v29, v33
	v_cvt_pk_bf16_f32 v17, v25, v17
	v_mad_i64_i32 v[20:21], s[4:5], v48, s63, v[116:117]
	v_ashrrev_i32_e32 v33, 31, v32
	v_mul_f32_e32 v22, v34, v22
	v_mul_f32_e32 v26, v28, v26
	v_cvt_pk_bf16_f32 v18, v22, v24
	v_cvt_pk_bf16_f32 v19, v26, v19
	global_store_dwordx4 v[20:21], v[16:19], off
	v_mov_b32_e32 v36, v0
	v_mov_b32_e32 v34, v4
	v_lshlrev_b64 v[16:17], 6, v[32:33]
	v_lshl_add_u64 v[28:29], s[18:19], 0, v[16:17]
	v_mov_b32_e32 v37, v8
	v_mov_b32_e32 v8, v1
	v_mov_b32_e32 v35, v12
	v_mov_b32_e32 v12, v5
	s_nop 0
	s_nop 0
	s_nop 1
	v_mov_b32_e32 v0, v6
	s_nop 1
	s_nop 1
	s_nop 1
	v_mov_b32_e32 v1, v14
	v_pk_mul_f32 v[16:17], v[34:35], v[192:193] op_sel_hi:[1,0]
	v_pk_mul_f32 v[18:19], v[36:37], v[192:193] op_sel_hi:[1,0]
	v_pk_mul_f32 v[12:13], v[12:13], v[192:193] op_sel_hi:[1,0]
	v_pk_mul_f32 v[8:9], v[8:9], v[192:193] op_sel_hi:[1,0]
	v_pk_mul_f32 v[0:1], v[0:1], v[192:193] op_sel_hi:[1,0]
	v_mul_f32_e32 v5, 0xbfb8aa3b, v17
	v_exp_f32_e32 v5, v5
	v_mul_f32_e32 v14, 0xbfb8aa3b, v13
	v_exp_f32_e32 v14, v14
	v_mul_f32_e32 v21, 0xbfb8aa3b, v1
	v_add_f32_e32 v5, 1.0, v5
	v_rcp_f32_e32 v5, v5
	v_add_f32_e32 v14, 1.0, v14
	v_rcp_f32_e32 v14, v14
	v_mul_f32_e32 v20, 0xbfb8aa3b, v9
	v_mul_f32_e32 v5, v17, v5
	v_mul_f32_e32 v5, v16, v5
	v_exp_f32_e32 v16, v21
	v_exp_f32_e32 v20, v20
	v_mul_f32_e32 v13, v13, v14
	v_mul_f32_e32 v17, v12, v13
	v_add_f32_e32 v12, 1.0, v16
	v_rcp_f32_e32 v14, v12
	v_mov_b32_e32 v12, v2
	v_mov_b32_e32 v13, v10
	v_add_f32_e32 v20, 1.0, v20
	v_pk_mul_f32 v[12:13], v[12:13], v[192:193] op_sel_hi:[1,0]
	v_rcp_f32_e32 v20, v20
	v_mul_f32_e32 v2, 0xbfb8aa3b, v13
	v_exp_f32_e32 v2, v2
	v_mul_f32_e32 v1, v1, v14
	v_mul_f32_e32 v9, v9, v20
	v_mul_f32_e32 v8, v8, v9
	v_mul_f32_e32 v9, v0, v1
	v_add_f32_e32 v0, 1.0, v2
	v_mov_b32_e32 v14, v7
	v_rcp_f32_e32 v16, v0
	v_pk_mul_f32 v[0:1], v[14:15], v[192:193] op_sel_hi:[1,0]
	v_mov_b32_e32 v10, v3
	v_mul_f32_e32 v2, 0xbfb8aa3b, v1
	v_exp_f32_e32 v7, v2
	v_pk_mul_f32 v[2:3], v[10:11], v[192:193] op_sel_hi:[1,0]
	v_mul_f32_e32 v6, 0xbfb8aa3b, v19
	v_mul_f32_e32 v4, 0xbfb8aa3b, v3
	v_exp_f32_e32 v4, v4
	v_exp_f32_e32 v6, v6
	v_add_f32_e32 v7, 1.0, v7
	v_rcp_f32_e32 v7, v7
	v_add_f32_e32 v4, 1.0, v4
	v_add_f32_e32 v6, 1.0, v6
	v_rcp_f32_e32 v4, v4
	v_rcp_f32_e32 v6, v6
	v_mul_f32_e32 v1, v1, v7
	v_mul_f32_e32 v1, v0, v1
	v_mul_f32_e32 v0, v3, v4
	v_mul_f32_e32 v6, v19, v6
	v_mul_f32_e32 v10, v13, v16
	v_mul_f32_e32 v3, v2, v0
	v_cvt_pk_bf16_f32 v0, v5, v17
	v_mad_i64_i32 v[4:5], s[4:5], v32, s63, v[116:117]
	s_andn2_b64 vcc, exec, s[2:3]
	s_mov_b64 s[2:3], -1
	v_mul_f32_e32 v6, v18, v6
	v_mul_f32_e32 v10, v12, v10
	v_cvt_pk_bf16_f32 v1, v9, v1
	v_cvt_pk_bf16_f32 v2, v6, v8
	v_cvt_pk_bf16_f32 v3, v10, v3
	global_store_dwordx4 v[4:5], v[0:3], off
	s_cbranch_vccnz .LBB0_1253
	s_andn2_b64 vcc, exec, s[10:11]
	s_cbranch_vccnz .LBB0_1252
	s_barrier
	s_branch .LBB0_1252
